# residual GEMM epilogues (out-projection, FFN down): next column group's residual-row loads issued one group ahead into free VGPRs (two groups in flight instead of one)
# speedup vs baseline: 1.0065x; 1.0065x over previous
;     __device__ __forceinline__ void operator()(const pg8::f32x4 (&acc)[2][2][4][2], const pg8::Unit& u, int wr, int wc, int fr, int fq) const {
;         const int row0 = u.pm * 256 + wr * 64 + fr, b = row0 >> 12;
;         const float* gt = modl + (size_t)b * 6144 + gidx * 1024;
; #pragma unroll
;         for (int bj = 0; bj < 2; ++bj)
; #pragma unroll
;             for (int n = 0; n < 2; ++n) {
;                 const int col = u.pn * 256 + bj * 128 + wc * 32 + n * 16 + fq * 4;
;                 const pg8::f32x4 g4 = *(const pg8::f32x4*)(gt + col);
;                 pg8::f32x4 xv[2][4];
; #pragma unroll
;                 for (int ai = 0; ai < 2; ++ai)
; #pragma unroll
;                     for (int m = 0; m < 4; ++m) xv[ai][m] = *(const pg8::f32x4*)(xin + (size_t)(row0 + ai * 128 + m * 16) * 1024 + col);
; #pragma unroll
;                 for (int ai = 0; ai < 2; ++ai)
; #pragma unroll
;                     for (int m = 0; m < 4; ++m) *(pg8::f32x4*)(xout + (size_t)(row0 + ai * 128 + m * 16) * 1024 + col) = xv[ai][m] + g4 * acc[ai][bj][m][n];
;             }
.LBB0_490:
	s_lshl_b32 s18, s44, 8
	s_add_i32 s18, s18, s35
	v_or_b32_e32 v146, s18, v170
	s_ashr_i32 s18, s18, 12
	s_mul_hi_i32 s19, s18, 0x6000
	s_mulk_i32 s18, 0x6000
	s_add_u32 s18, s33, s18
	s_addc_u32 s19, s34, s19
	v_lshl_or_b32 v166, s43, 8, v172
	s_add_u32 s18, s18, 0x5000
	v_ashrrev_i32_e32 v167, 31, v166
	s_addc_u32 s19, s19, 0
	v_lshlrev_b64 v[148:149], 2, v[166:167]
	v_lshl_add_u64 v[136:137], s[18:19], 0, v[148:149]
	v_ashrrev_i32_e32 v147, 31, v146
	global_load_dwordx4 v[138:141], v[136:137], off
	v_lshl_add_u64 v[168:169], s[8:9], 0, v[148:149]
	v_lshlrev_b64 v[200:201], 12, v[146:147]
	v_or_b32_e32 v136, 16, v146
	v_lshl_add_u64 v[162:163], v[168:169], 0, v[200:201]
	v_ashrrev_i32_e32 v137, 31, v136
	global_load_dwordx4 v[142:145], v[162:163], off
	v_lshlrev_b64 v[202:203], 12, v[136:137]
	v_or_b32_e32 v154, 32, v146
	v_lshl_add_u64 v[136:137], v[168:169], 0, v[202:203]
	v_ashrrev_i32_e32 v155, 31, v154
	global_load_dwordx4 v[150:153], v[136:137], off
	v_lshlrev_b64 v[208:209], 12, v[154:155]
	v_or_b32_e32 v146, 48, v146
	v_lshl_add_u64 v[154:155], v[168:169], 0, v[208:209]
	v_ashrrev_i32_e32 v147, 31, v146
	global_load_dwordx4 v[174:177], v[154:155], off
	v_lshlrev_b64 v[146:147], 12, v[146:147]
	v_lshl_add_u64 v[156:157], v[168:169], 0, v[146:147]
	s_mov_b64 s[20:21], 0x80000
	global_load_dwordx4 v[178:181], v[156:157], off
	v_lshl_add_u64 v[210:211], v[200:201], 0, s[20:21]
	v_lshl_add_u64 v[158:159], v[168:169], 0, v[210:211]
	s_mov_b64 s[20:21], 0x90000
	global_load_dwordx4 v[182:185], v[158:159], off
	v_lshl_add_u64 v[212:213], v[200:201], 0, s[20:21]
	v_lshl_add_u64 v[160:161], v[168:169], 0, v[212:213]
	s_mov_b64 s[20:21], 0xa0000
	global_load_dwordx4 v[186:189], v[160:161], off
	v_lshl_add_u64 v[214:215], v[200:201], 0, s[20:21]
	s_mov_b64 s[20:21], 0xb0000
	v_lshl_add_u64 v[164:165], v[168:169], 0, v[214:215]
	v_lshl_add_u64 v[216:217], v[200:201], 0, s[20:21]
	global_load_dwordx4 v[190:193], v[164:165], off
	v_lshl_add_u64 v[168:169], v[168:169], 0, v[216:217]
	global_load_dwordx4 v[194:197], v[168:169], off
	s_and_b64 vcc, exec, s[4:5]
	global_load_dwordx4 v[220:223], v[162:163], off offset:64
	global_load_dwordx4 v[224:227], v[136:137], off offset:64
	global_load_dwordx4 v[228:231], v[154:155], off offset:64
	global_load_dwordx4 v[232:235], v[156:157], off offset:64
	global_load_dwordx4 v[236:239], v[158:159], off offset:64
	global_load_dwordx4 v[240:243], v[160:161], off offset:64
	global_load_dwordx4 v[244:247], v[164:165], off offset:64
	global_load_dwordx4 v[248:251], v[168:169], off offset:64
	s_waitcnt vmcnt(8)
	v_pk_fma_f32 v[142:143], v[128:129], v[138:139], v[142:143]
	v_lshl_add_u64 v[128:129], s[8:9], 0, v[200:201]
	v_pk_fma_f32 v[144:145], v[130:131], v[140:141], v[144:145]
	v_lshl_add_u64 v[128:129], v[128:129], 0, v[148:149]
	global_store_dwordx4 v[128:129], v[142:145], off
	v_pk_fma_f32 v[102:103], v[102:103], v[140:141], v[196:197]
	s_nop 0
	v_pk_fma_f32 v[142:143], v[124:125], v[138:139], v[150:151]
	v_lshl_add_u64 v[124:125], s[8:9], 0, v[202:203]
	v_pk_fma_f32 v[144:145], v[126:127], v[140:141], v[152:153]
	v_lshl_add_u64 v[124:125], v[124:125], 0, v[148:149]
	global_store_dwordx4 v[124:125], v[142:145], off
	v_pk_fma_f32 v[100:101], v[100:101], v[138:139], v[194:195]
	s_nop 0
	v_pk_fma_f32 v[142:143], v[120:121], v[138:139], v[174:175]
	v_lshl_add_u64 v[120:121], s[8:9], 0, v[208:209]
	v_pk_fma_f32 v[144:145], v[122:123], v[140:141], v[176:177]
	v_lshl_add_u64 v[120:121], v[120:121], 0, v[148:149]
	global_store_dwordx4 v[120:121], v[142:145], off
	s_nop 1
	v_pk_fma_f32 v[142:143], v[116:117], v[138:139], v[178:179]
	v_lshl_add_u64 v[116:117], s[8:9], 0, v[146:147]
	v_pk_fma_f32 v[144:145], v[118:119], v[140:141], v[180:181]
	v_lshl_add_u64 v[116:117], v[116:117], 0, v[148:149]
	global_store_dwordx4 v[116:117], v[142:145], off
	s_nop 1
	v_pk_fma_f32 v[142:143], v[112:113], v[138:139], v[182:183]
	v_lshl_add_u64 v[112:113], s[8:9], 0, v[210:211]
	v_pk_fma_f32 v[144:145], v[114:115], v[140:141], v[184:185]
	v_lshl_add_u64 v[112:113], v[112:113], 0, v[148:149]
	global_store_dwordx4 v[112:113], v[142:145], off
	s_nop 1
	v_pk_fma_f32 v[142:143], v[108:109], v[138:139], v[186:187]
	v_lshl_add_u64 v[108:109], s[8:9], 0, v[212:213]
	v_pk_fma_f32 v[144:145], v[110:111], v[140:141], v[188:189]
	v_lshl_add_u64 v[108:109], v[108:109], 0, v[148:149]
	global_store_dwordx4 v[108:109], v[142:145], off
	s_nop 1
	v_pk_fma_f32 v[144:145], v[106:107], v[140:141], v[192:193]
	v_lshl_add_u64 v[106:107], s[8:9], 0, v[216:217]
	v_lshl_add_u64 v[106:107], v[106:107], 0, v[148:149]
	v_pk_fma_f32 v[142:143], v[104:105], v[138:139], v[190:191]
	v_lshl_add_u64 v[104:105], s[8:9], 0, v[214:215]
	global_store_dwordx4 v[106:107], v[100:103], off
	v_lshl_add_u64 v[104:105], v[104:105], 0, v[148:149]
	global_store_dwordx4 v[104:105], v[142:145], off
	v_or_b32_e32 v100, 16, v166
	v_ashrrev_i32_e32 v101, 31, v100
	v_lshl_add_u64 v[100:101], v[100:101], 2, s[18:19]
	global_load_dwordx4 v[100:103], v[100:101], off
	s_nop 0
	global_load_dwordx4 v[142:145], v[162:163], off offset:512
	global_load_dwordx4 v[150:153], v[136:137], off offset:512
	global_load_dwordx4 v[174:177], v[154:155], off offset:512
	global_load_dwordx4 v[178:181], v[156:157], off offset:512
	global_load_dwordx4 v[182:185], v[158:159], off offset:512
	global_load_dwordx4 v[186:189], v[160:161], off offset:512
	global_load_dwordx4 v[190:193], v[164:165], off offset:512
	global_load_dwordx4 v[194:197], v[168:169], off offset:512
	s_waitcnt vmcnt(8)
;     __device__ __forceinline__ void operator()(const pg8::f32x4 (&acc)[2][2][4][2], const pg8::Unit& u, int wr, int wc, int fr, int fq) const {
;         const int row0 = u.pm * 256 + wr * 64 + fr, b = row0 >> 12;
;         const float* gt = modl + (size_t)b * 6144 + gidx * 1024;
; #pragma unroll
;         for (int bj = 0; bj < 2; ++bj)
; #pragma unroll
;             for (int n = 0; n < 2; ++n) {
;                 const int col = u.pn * 256 + bj * 128 + wc * 32 + n * 16 + fq * 4;
;                 const pg8::f32x4 g4 = *(const pg8::f32x4*)(gt + col);
;                 pg8::f32x4 xv[2][4];
; #pragma unroll
;                 for (int ai = 0; ai < 2; ++ai)
; #pragma unroll
;                     for (int m = 0; m < 4; ++m) xv[ai][m] = *(const pg8::f32x4*)(xin + (size_t)(row0 + ai * 128 + m * 16) * 1024 + col);
; #pragma unroll
;                 for (int ai = 0; ai < 2; ++ai)
; #pragma unroll
;                     for (int m = 0; m < 4; ++m) *(pg8::f32x4*)(xout + (size_t)(row0 + ai * 128 + m * 16) * 1024 + col) = xv[ai][m] + g4 * acc[ai][bj][m][n];
;             }
	v_pk_fma_f32 v[98:99], v[98:99], v[102:103], v[222:223]
	v_pk_fma_f32 v[96:97], v[96:97], v[100:101], v[220:221]
	s_waitcnt vmcnt(8)
	v_pk_fma_f32 v[94:95], v[94:95], v[102:103], v[226:227]
	v_pk_fma_f32 v[92:93], v[92:93], v[100:101], v[224:225]
	s_waitcnt vmcnt(8)
	v_pk_fma_f32 v[90:91], v[90:91], v[102:103], v[230:231]
	v_pk_fma_f32 v[88:89], v[88:89], v[100:101], v[228:229]
	s_waitcnt vmcnt(8)
	v_pk_fma_f32 v[86:87], v[86:87], v[102:103], v[234:235]
	s_waitcnt vmcnt(8)
	v_pk_fma_f32 v[70:71], v[70:71], v[102:103], v[250:251]
	v_pk_fma_f32 v[68:69], v[68:69], v[100:101], v[248:249]
	global_store_dwordx4 v[106:107], v[68:71], off offset:64
	v_pk_fma_f32 v[84:85], v[84:85], v[100:101], v[232:233]
	v_pk_fma_f32 v[82:83], v[82:83], v[102:103], v[238:239]
	v_or_b32_e32 v68, 0x80, v166
	v_pk_fma_f32 v[80:81], v[80:81], v[100:101], v[236:237]
	v_pk_fma_f32 v[78:79], v[78:79], v[102:103], v[242:243]
	v_pk_fma_f32 v[76:77], v[76:77], v[100:101], v[240:241]
	v_pk_fma_f32 v[74:75], v[74:75], v[102:103], v[246:247]
	v_pk_fma_f32 v[72:73], v[72:73], v[100:101], v[244:245]
	v_ashrrev_i32_e32 v69, 31, v68
	global_store_dwordx4 v[128:129], v[96:99], off offset:64
	global_store_dwordx4 v[124:125], v[92:95], off offset:64
	global_store_dwordx4 v[120:121], v[88:91], off offset:64
	global_store_dwordx4 v[116:117], v[84:87], off offset:64
	global_store_dwordx4 v[112:113], v[80:83], off offset:64
	global_store_dwordx4 v[108:109], v[76:79], off offset:64
	global_store_dwordx4 v[104:105], v[72:75], off offset:64
	v_lshl_add_u64 v[68:69], v[68:69], 2, s[18:19]
	global_load_dwordx4 v[68:71], v[68:69], off
	s_nop 0
	global_load_dwordx4 v[220:223], v[162:163], off offset:576
	global_load_dwordx4 v[224:227], v[136:137], off offset:576
	global_load_dwordx4 v[228:231], v[154:155], off offset:576
	global_load_dwordx4 v[232:235], v[156:157], off offset:576
	global_load_dwordx4 v[236:239], v[158:159], off offset:576
	global_load_dwordx4 v[240:243], v[160:161], off offset:576
	global_load_dwordx4 v[244:247], v[164:165], off offset:576
	global_load_dwordx4 v[248:251], v[168:169], off offset:576
	s_waitcnt vmcnt(8)
	v_pk_fma_f32 v[66:67], v[66:67], v[70:71], v[144:145]
	v_pk_fma_f32 v[64:65], v[64:65], v[68:69], v[142:143]
	s_waitcnt vmcnt(8)
	v_pk_fma_f32 v[62:63], v[62:63], v[70:71], v[152:153]
	v_pk_fma_f32 v[60:61], v[60:61], v[68:69], v[150:151]
	s_waitcnt vmcnt(8)
	v_pk_fma_f32 v[58:59], v[58:59], v[70:71], v[176:177]
	v_pk_fma_f32 v[56:57], v[56:57], v[68:69], v[174:175]
	s_waitcnt vmcnt(8)
	v_pk_fma_f32 v[54:55], v[54:55], v[70:71], v[180:181]
	s_waitcnt vmcnt(8)
	v_pk_fma_f32 v[38:39], v[38:39], v[70:71], v[196:197]
	v_pk_fma_f32 v[36:37], v[36:37], v[68:69], v[194:195]
	global_store_dwordx4 v[106:107], v[36:39], off offset:512
	v_pk_fma_f32 v[52:53], v[52:53], v[68:69], v[178:179]
	v_pk_fma_f32 v[50:51], v[50:51], v[70:71], v[184:185]
	v_or_b32_e32 v36, 0x90, v166
	v_pk_fma_f32 v[48:49], v[48:49], v[68:69], v[182:183]
	v_pk_fma_f32 v[46:47], v[46:47], v[70:71], v[188:189]
	v_pk_fma_f32 v[44:45], v[44:45], v[68:69], v[186:187]
	v_pk_fma_f32 v[42:43], v[42:43], v[70:71], v[192:193]
	v_pk_fma_f32 v[40:41], v[40:41], v[68:69], v[190:191]
	v_ashrrev_i32_e32 v37, 31, v36
	global_store_dwordx4 v[128:129], v[64:67], off offset:512
	global_store_dwordx4 v[124:125], v[60:63], off offset:512
	global_store_dwordx4 v[120:121], v[56:59], off offset:512
	global_store_dwordx4 v[116:117], v[52:55], off offset:512
	global_store_dwordx4 v[112:113], v[48:51], off offset:512
	global_store_dwordx4 v[108:109], v[44:47], off offset:512
	global_store_dwordx4 v[104:105], v[40:43], off offset:512
	v_lshl_add_u64 v[36:37], v[36:37], 2, s[18:19]
	global_load_dwordx4 v[36:39], v[36:37], off
	s_nop 0
	s_mov_b64 s[18:19], -1
	s_waitcnt vmcnt(0)
	v_pk_fma_f32 v[34:35], v[34:35], v[38:39], v[222:223]
	v_pk_fma_f32 v[32:33], v[32:33], v[36:37], v[220:221]
	s_waitcnt vmcnt(0)
	v_pk_fma_f32 v[30:31], v[30:31], v[38:39], v[226:227]
	v_pk_fma_f32 v[28:29], v[28:29], v[36:37], v[224:225]
	s_waitcnt vmcnt(0)
	v_pk_fma_f32 v[26:27], v[26:27], v[38:39], v[230:231]
	v_pk_fma_f32 v[24:25], v[24:25], v[36:37], v[228:229]
	s_waitcnt vmcnt(0)
	v_pk_fma_f32 v[22:23], v[22:23], v[38:39], v[234:235]
	v_pk_fma_f32 v[20:21], v[20:21], v[36:37], v[232:233]
	s_waitcnt vmcnt(0)
	v_pk_fma_f32 v[18:19], v[18:19], v[38:39], v[238:239]
	v_pk_fma_f32 v[16:17], v[16:17], v[36:37], v[236:237]
	s_waitcnt vmcnt(0)
	v_pk_fma_f32 v[14:15], v[14:15], v[38:39], v[242:243]
	v_pk_fma_f32 v[12:13], v[12:13], v[36:37], v[240:241]
	s_waitcnt vmcnt(0)
	v_pk_fma_f32 v[10:11], v[10:11], v[38:39], v[246:247]
	v_pk_fma_f32 v[8:9], v[8:9], v[36:37], v[244:245]
	s_waitcnt vmcnt(0)
	v_pk_fma_f32 v[6:7], v[6:7], v[38:39], v[250:251]
	v_pk_fma_f32 v[4:5], v[4:5], v[36:37], v[248:249]
	global_store_dwordx4 v[128:129], v[32:35], off offset:576
	global_store_dwordx4 v[124:125], v[28:31], off offset:576
	global_store_dwordx4 v[120:121], v[24:27], off offset:576
	global_store_dwordx4 v[116:117], v[20:23], off offset:576
	global_store_dwordx4 v[112:113], v[16:19], off offset:576
	global_store_dwordx4 v[108:109], v[12:15], off offset:576
	global_store_dwordx4 v[104:105], v[8:11], off offset:576
	global_store_dwordx4 v[106:107], v[4:7], off offset:576
	s_cbranch_vccnz .LBB0_475
	s_andn2_b64 vcc, exec, s[10:11]
	s_cbranch_vccnz .LBB0_474
	s_barrier
	s_branch .LBB0_474

;     __device__ __forceinline__ void operator()(const pg8::f32x4 (&acc)[2][2][4][2], const pg8::Unit& u, int wr, int wc, int fr, int fq) const {
;         const int row0 = u.pm * 256 + wr * 64 + fr, b = row0 >> 12;
;         const float* gt = modl + (size_t)b * 6144 + gidx * 1024;
; #pragma unroll
;         for (int bj = 0; bj < 2; ++bj)
; #pragma unroll
;             for (int n = 0; n < 2; ++n) {
;                 const int col = u.pn * 256 + bj * 128 + wc * 32 + n * 16 + fq * 4;
;                 const pg8::f32x4 g4 = *(const pg8::f32x4*)(gt + col);
;                 pg8::f32x4 xv[2][4];
; #pragma unroll
;                 for (int ai = 0; ai < 2; ++ai)
; #pragma unroll
;                     for (int m = 0; m < 4; ++m) xv[ai][m] = *(const pg8::f32x4*)(xin + (size_t)(row0 + ai * 128 + m * 16) * 1024 + col);
; #pragma unroll
;                 for (int ai = 0; ai < 2; ++ai)
; #pragma unroll
;                     for (int m = 0; m < 4; ++m) *(pg8::f32x4*)(xout + (size_t)(row0 + ai * 128 + m * 16) * 1024 + col) = xv[ai][m] + g4 * acc[ai][bj][m][n];
;             }
.LBB0_539:
	s_lshl_b32 s17, s48, 8
	s_add_i32 s17, s17, s43
	v_or_b32_e32 v146, s17, v170
	s_ashr_i32 s17, s17, 12
	s_mul_hi_i32 s19, s17, 0x6000
	s_mulk_i32 s17, 0x6000
	s_add_u32 s17, s39, s17
	s_addc_u32 s19, s42, s19
	v_lshl_or_b32 v168, s47, 8, v172
	s_add_u32 s24, s17, 0x2000
	v_ashrrev_i32_e32 v169, 31, v168
	s_addc_u32 s25, s19, 0
	v_lshlrev_b64 v[148:149], 2, v[168:169]
	v_ashrrev_i32_e32 v147, 31, v146
	v_lshl_add_u64 v[136:137], s[24:25], 0, v[148:149]
	v_lshl_add_u64 v[166:167], s[10:11], 0, v[148:149]
	v_lshlrev_b64 v[200:201], 12, v[146:147]
	v_or_b32_e32 v150, 16, v146
	global_load_dwordx4 v[138:141], v[136:137], off
	v_lshl_add_u64 v[136:137], v[166:167], 0, v[200:201]
	v_ashrrev_i32_e32 v151, 31, v150
	global_load_dwordx4 v[142:145], v[136:137], off
	v_lshlrev_b64 v[202:203], 12, v[150:151]
	v_or_b32_e32 v156, 32, v146
	v_lshl_add_u64 v[154:155], v[166:167], 0, v[202:203]
	v_ashrrev_i32_e32 v157, 31, v156
	global_load_dwordx4 v[150:153], v[154:155], off
	v_lshlrev_b64 v[208:209], 12, v[156:157]
	v_or_b32_e32 v146, 48, v146
	v_lshl_add_u64 v[156:157], v[166:167], 0, v[208:209]
	v_ashrrev_i32_e32 v147, 31, v146
	global_load_dwordx4 v[174:177], v[156:157], off
	v_lshlrev_b64 v[146:147], 12, v[146:147]
	v_lshl_add_u64 v[158:159], v[166:167], 0, v[146:147]
	s_mov_b64 s[26:27], 0x80000
	global_load_dwordx4 v[178:181], v[158:159], off
	v_lshl_add_u64 v[210:211], v[200:201], 0, s[26:27]
	v_lshl_add_u64 v[160:161], v[166:167], 0, v[210:211]
	s_mov_b64 s[26:27], 0x90000
	global_load_dwordx4 v[182:185], v[160:161], off
	v_lshl_add_u64 v[212:213], v[200:201], 0, s[26:27]
	s_mov_b64 s[26:27], 0xa0000
	v_lshl_add_u64 v[162:163], v[166:167], 0, v[212:213]
	v_lshl_add_u64 v[214:215], v[200:201], 0, s[26:27]
	s_mov_b64 s[26:27], 0xb0000
	global_load_dwordx4 v[186:189], v[162:163], off
	v_lshl_add_u64 v[216:217], v[200:201], 0, s[26:27]
	v_lshl_add_u64 v[164:165], v[166:167], 0, v[214:215]
	v_lshl_add_u64 v[166:167], v[166:167], 0, v[216:217]
	global_load_dwordx4 v[190:193], v[164:165], off
	global_load_dwordx4 v[194:197], v[166:167], off
	s_andn2_b64 vcc, exec, s[4:5]
	s_mov_b32 s30, 0x3a800000
	global_load_dwordx4 v[220:223], v[136:137], off offset:64
	global_load_dwordx4 v[224:227], v[154:155], off offset:64
	global_load_dwordx4 v[228:231], v[156:157], off offset:64
	global_load_dwordx4 v[232:235], v[158:159], off offset:64
	global_load_dwordx4 v[236:239], v[160:161], off offset:64
	global_load_dwordx4 v[240:243], v[162:163], off offset:64
	global_load_dwordx4 v[244:247], v[164:165], off offset:64
	global_load_dwordx4 v[248:251], v[166:167], off offset:64
	s_waitcnt vmcnt(8)
	v_pk_fma_f32 v[142:143], v[128:129], v[138:139], v[142:143]
	v_lshl_add_u64 v[128:129], s[8:9], 0, v[200:201]
	v_pk_fma_f32 v[144:145], v[130:131], v[140:141], v[144:145]
	v_lshl_add_u64 v[128:129], v[128:129], 0, v[148:149]
	global_store_dwordx4 v[128:129], v[142:145], off
	s_nop 1
	v_pk_fma_f32 v[142:143], v[124:125], v[138:139], v[150:151]
	v_lshl_add_u64 v[124:125], s[8:9], 0, v[202:203]
	v_pk_fma_f32 v[144:145], v[126:127], v[140:141], v[152:153]
	v_lshl_add_u64 v[124:125], v[124:125], 0, v[148:149]
	global_store_dwordx4 v[124:125], v[142:145], off
	s_nop 1
	v_pk_fma_f32 v[142:143], v[120:121], v[138:139], v[174:175]
	v_lshl_add_u64 v[120:121], s[8:9], 0, v[208:209]
	v_pk_fma_f32 v[144:145], v[122:123], v[140:141], v[176:177]
	v_lshl_add_u64 v[120:121], v[120:121], 0, v[148:149]
	global_store_dwordx4 v[120:121], v[142:145], off
	s_nop 1
	v_pk_fma_f32 v[142:143], v[116:117], v[138:139], v[178:179]
	v_lshl_add_u64 v[116:117], s[8:9], 0, v[146:147]
	v_pk_fma_f32 v[144:145], v[118:119], v[140:141], v[180:181]
	v_lshl_add_u64 v[116:117], v[116:117], 0, v[148:149]
	global_store_dwordx4 v[116:117], v[142:145], off
	s_nop 1
	v_pk_fma_f32 v[142:143], v[112:113], v[138:139], v[182:183]
	v_lshl_add_u64 v[112:113], s[8:9], 0, v[210:211]
	v_pk_fma_f32 v[144:145], v[114:115], v[140:141], v[184:185]
	v_lshl_add_u64 v[112:113], v[112:113], 0, v[148:149]
	global_store_dwordx4 v[112:113], v[142:145], off
	s_nop 1
	v_pk_fma_f32 v[142:143], v[108:109], v[138:139], v[186:187]
	v_lshl_add_u64 v[108:109], s[8:9], 0, v[212:213]
	v_pk_fma_f32 v[144:145], v[110:111], v[140:141], v[188:189]
	v_lshl_add_u64 v[108:109], v[108:109], 0, v[148:149]
	global_store_dwordx4 v[108:109], v[142:145], off
	s_nop 1
	v_pk_fma_f32 v[144:145], v[106:107], v[140:141], v[192:193]
	v_pk_fma_f32 v[142:143], v[104:105], v[138:139], v[190:191]
	v_lshl_add_u64 v[104:105], s[8:9], 0, v[214:215]
	v_pk_fma_f32 v[140:141], v[102:103], v[140:141], v[196:197]
	v_pk_fma_f32 v[138:139], v[100:101], v[138:139], v[194:195]
	v_lshl_add_u64 v[100:101], s[8:9], 0, v[216:217]
	v_or_b32_e32 v102, 16, v168
	v_lshl_add_u64 v[104:105], v[104:105], 0, v[148:149]
	v_lshl_add_u64 v[100:101], v[100:101], 0, v[148:149]
	v_ashrrev_i32_e32 v103, 31, v102
	global_store_dwordx4 v[104:105], v[142:145], off
	global_store_dwordx4 v[100:101], v[138:141], off
	v_lshl_add_u64 v[102:103], v[102:103], 2, s[24:25]
	global_load_dwordx4 v[138:141], v[102:103], off
	global_load_dwordx4 v[142:145], v[136:137], off offset:512
	global_load_dwordx4 v[150:153], v[154:155], off offset:512
	global_load_dwordx4 v[174:177], v[156:157], off offset:512
	global_load_dwordx4 v[178:181], v[158:159], off offset:512
	global_load_dwordx4 v[182:185], v[160:161], off offset:512
	global_load_dwordx4 v[186:189], v[162:163], off offset:512
	global_load_dwordx4 v[190:193], v[164:165], off offset:512
	global_load_dwordx4 v[194:197], v[166:167], off offset:512
	s_waitcnt vmcnt(8)
;     __device__ __forceinline__ void operator()(const pg8::f32x4 (&acc)[2][2][4][2], const pg8::Unit& u, int wr, int wc, int fr, int fq) const {
;         const int row0 = u.pm * 256 + wr * 64 + fr, b = row0 >> 12;
;         const float* gt = modl + (size_t)b * 6144 + gidx * 1024;
; #pragma unroll
;         for (int bj = 0; bj < 2; ++bj)
; #pragma unroll
;             for (int n = 0; n < 2; ++n) {
;                 const int col = u.pn * 256 + bj * 128 + wc * 32 + n * 16 + fq * 4;
;                 const pg8::f32x4 g4 = *(const pg8::f32x4*)(gt + col);
;                 pg8::f32x4 xv[2][4];
; #pragma unroll
;                 for (int ai = 0; ai < 2; ++ai)
; #pragma unroll
;                     for (int m = 0; m < 4; ++m) xv[ai][m] = *(const pg8::f32x4*)(xin + (size_t)(row0 + ai * 128 + m * 16) * 1024 + col);
; #pragma unroll
;                 for (int ai = 0; ai < 2; ++ai)
; #pragma unroll
;                     for (int m = 0; m < 4; ++m) *(pg8::f32x4*)(xout + (size_t)(row0 + ai * 128 + m * 16) * 1024 + col) = xv[ai][m] + g4 * acc[ai][bj][m][n];
;             }
	v_pk_fma_f32 v[98:99], v[98:99], v[140:141], v[222:223]
	v_pk_fma_f32 v[96:97], v[96:97], v[138:139], v[220:221]
	s_waitcnt vmcnt(8)
	v_pk_fma_f32 v[94:95], v[94:95], v[140:141], v[226:227]
	v_pk_fma_f32 v[92:93], v[92:93], v[138:139], v[224:225]
	s_waitcnt vmcnt(8)
	v_pk_fma_f32 v[90:91], v[90:91], v[140:141], v[230:231]
	v_pk_fma_f32 v[88:89], v[88:89], v[138:139], v[228:229]
	s_waitcnt vmcnt(8)
	v_pk_fma_f32 v[86:87], v[86:87], v[140:141], v[234:235]
	s_waitcnt vmcnt(8)
	v_pk_fma_f32 v[70:71], v[70:71], v[140:141], v[250:251]
	v_pk_fma_f32 v[68:69], v[68:69], v[138:139], v[248:249]
	global_store_dwordx4 v[100:101], v[68:71], off offset:64
	v_pk_fma_f32 v[84:85], v[84:85], v[138:139], v[232:233]
	v_pk_fma_f32 v[82:83], v[82:83], v[140:141], v[238:239]
	v_or_b32_e32 v68, 0x80, v168
	v_pk_fma_f32 v[80:81], v[80:81], v[138:139], v[236:237]
	v_pk_fma_f32 v[78:79], v[78:79], v[140:141], v[242:243]
	v_pk_fma_f32 v[76:77], v[76:77], v[138:139], v[240:241]
	v_pk_fma_f32 v[74:75], v[74:75], v[140:141], v[246:247]
	v_pk_fma_f32 v[72:73], v[72:73], v[138:139], v[244:245]
	v_ashrrev_i32_e32 v69, 31, v68
	global_store_dwordx4 v[128:129], v[96:99], off offset:64
	global_store_dwordx4 v[124:125], v[92:95], off offset:64
	global_store_dwordx4 v[120:121], v[88:91], off offset:64
	global_store_dwordx4 v[116:117], v[84:87], off offset:64
	global_store_dwordx4 v[112:113], v[80:83], off offset:64
	global_store_dwordx4 v[108:109], v[76:79], off offset:64
	global_store_dwordx4 v[104:105], v[72:75], off offset:64
	v_lshl_add_u64 v[68:69], v[68:69], 2, s[24:25]
	global_load_dwordx4 v[68:71], v[68:69], off
	s_nop 0
	global_load_dwordx4 v[220:223], v[136:137], off offset:576
	global_load_dwordx4 v[224:227], v[154:155], off offset:576
	global_load_dwordx4 v[228:231], v[156:157], off offset:576
	global_load_dwordx4 v[232:235], v[158:159], off offset:576
	global_load_dwordx4 v[236:239], v[160:161], off offset:576
	global_load_dwordx4 v[240:243], v[162:163], off offset:576
	global_load_dwordx4 v[244:247], v[164:165], off offset:576
	global_load_dwordx4 v[248:251], v[166:167], off offset:576
	s_waitcnt vmcnt(8)
	v_pk_fma_f32 v[66:67], v[66:67], v[70:71], v[144:145]
	v_pk_fma_f32 v[64:65], v[64:65], v[68:69], v[142:143]
	s_waitcnt vmcnt(8)
	v_pk_fma_f32 v[62:63], v[62:63], v[70:71], v[152:153]
	v_pk_fma_f32 v[60:61], v[60:61], v[68:69], v[150:151]
	s_waitcnt vmcnt(8)
	v_pk_fma_f32 v[58:59], v[58:59], v[70:71], v[176:177]
	v_pk_fma_f32 v[56:57], v[56:57], v[68:69], v[174:175]
	s_waitcnt vmcnt(8)
	v_pk_fma_f32 v[54:55], v[54:55], v[70:71], v[180:181]
	s_waitcnt vmcnt(8)
	v_pk_fma_f32 v[38:39], v[38:39], v[70:71], v[196:197]
	v_pk_fma_f32 v[36:37], v[36:37], v[68:69], v[194:195]
	global_store_dwordx4 v[100:101], v[36:39], off offset:512
	v_pk_fma_f32 v[52:53], v[52:53], v[68:69], v[178:179]
	v_pk_fma_f32 v[50:51], v[50:51], v[70:71], v[184:185]
	v_or_b32_e32 v36, 0x90, v168
	v_pk_fma_f32 v[48:49], v[48:49], v[68:69], v[182:183]
	v_pk_fma_f32 v[46:47], v[46:47], v[70:71], v[188:189]
	v_pk_fma_f32 v[44:45], v[44:45], v[68:69], v[186:187]
	v_pk_fma_f32 v[42:43], v[42:43], v[70:71], v[192:193]
	v_pk_fma_f32 v[40:41], v[40:41], v[68:69], v[190:191]
	v_ashrrev_i32_e32 v37, 31, v36
	global_store_dwordx4 v[128:129], v[64:67], off offset:512
	global_store_dwordx4 v[124:125], v[60:63], off offset:512
	global_store_dwordx4 v[120:121], v[56:59], off offset:512
	global_store_dwordx4 v[116:117], v[52:55], off offset:512
	global_store_dwordx4 v[112:113], v[48:51], off offset:512
	global_store_dwordx4 v[108:109], v[44:47], off offset:512
	global_store_dwordx4 v[104:105], v[40:43], off offset:512
	v_lshl_add_u64 v[36:37], v[36:37], 2, s[24:25]
	global_load_dwordx4 v[36:39], v[36:37], off
	s_nop 0
	s_mov_b64 s[24:25], -1
	s_waitcnt vmcnt(0)
	v_pk_fma_f32 v[34:35], v[34:35], v[38:39], v[222:223]
	v_pk_fma_f32 v[32:33], v[32:33], v[36:37], v[220:221]
	s_waitcnt vmcnt(0)
	v_pk_fma_f32 v[30:31], v[30:31], v[38:39], v[226:227]
	v_pk_fma_f32 v[28:29], v[28:29], v[36:37], v[224:225]
	s_waitcnt vmcnt(0)
	v_pk_fma_f32 v[26:27], v[26:27], v[38:39], v[230:231]
	v_pk_fma_f32 v[24:25], v[24:25], v[36:37], v[228:229]
	s_waitcnt vmcnt(0)
	v_pk_fma_f32 v[22:23], v[22:23], v[38:39], v[234:235]
	v_pk_fma_f32 v[20:21], v[20:21], v[36:37], v[232:233]
	s_waitcnt vmcnt(0)
	v_pk_fma_f32 v[18:19], v[18:19], v[38:39], v[238:239]
	v_pk_fma_f32 v[16:17], v[16:17], v[36:37], v[236:237]
	s_waitcnt vmcnt(0)
	v_pk_fma_f32 v[14:15], v[14:15], v[38:39], v[242:243]
	v_pk_fma_f32 v[12:13], v[12:13], v[36:37], v[240:241]
	s_waitcnt vmcnt(0)
	v_pk_fma_f32 v[10:11], v[10:11], v[38:39], v[246:247]
	v_pk_fma_f32 v[8:9], v[8:9], v[36:37], v[244:245]
	s_waitcnt vmcnt(0)
	v_pk_fma_f32 v[6:7], v[6:7], v[38:39], v[250:251]
	v_pk_fma_f32 v[4:5], v[4:5], v[36:37], v[248:249]
	global_store_dwordx4 v[128:129], v[32:35], off offset:576
	global_store_dwordx4 v[124:125], v[28:31], off offset:576
	global_store_dwordx4 v[120:121], v[24:27], off offset:576
	global_store_dwordx4 v[116:117], v[20:23], off offset:576
	global_store_dwordx4 v[112:113], v[16:19], off offset:576
	global_store_dwordx4 v[108:109], v[12:15], off offset:576
	global_store_dwordx4 v[104:105], v[8:11], off offset:576
	global_store_dwordx4 v[100:101], v[4:7], off offset:576
	s_cbranch_vccnz .LBB0_528
	s_andn2_b64 vcc, exec, s[12:13]
	s_cbranch_vccnz .LBB0_527
	s_barrier
	s_branch .LBB0_527
